# attention KV loop rewritten by hand (K/V fragments prefetched, V fragments read once for both query sub-tiles, scalar row sums); odd wave slots start the attention item 1280 cycles late at raised prio
# speedup vs baseline: 1.0131x; 1.0131x over previous
.LBB0_340:
	s_setprio 0
	s_waitcnt vmcnt(0)
	s_barrier
	s_mov_b64 s[0:1], exec
	v_readlane_b32 s2, v252, 9
	v_readlane_b32 s3, v252, 10
	s_and_b64 s[2:3], s[0:1], s[2:3]
	s_mov_b64 exec, s[2:3]
	s_cbranch_execz .LBB0_403
	v_readlane_b32 s2, v255, 12
	s_waitcnt vmcnt(0) expcnt(0) lgkmcnt(0)
	s_nop 0
	v_mov_b32_e32 v0, s2
	ds_read_b32 v2, v0
	v_readlane_b32 s2, v255, 13
	s_waitcnt lgkmcnt(0)
	v_cmp_ne_u32_e32 vcc, 0, v2
	v_mov_b32_e32 v0, s2
	ds_read_b32 v0, v0
	s_cbranch_vccnz .LBB0_367
	s_mov_b32 s2, 1
	s_branch .LBB0_355

.LBB0_344:
	s_getreg_b32 s98, hwreg(HW_REG_HW_ID, 0, 4)
	s_bitcmp1_b32 s98, 0
	s_cbranch_scc0 .Lattn_nosleep
	s_sleep 20
	s_setprio 1

.LBB0_346:
	s_cmp_lg_u32 s1, 64
	s_cselect_b64 s[28:29], -1, 0
	s_cbranch_scc0 .Lat_skipld
	v_lshl_add_u64 v[214:215], s[88:89], 0, v[208:209]
	v_lshl_add_u64 v[216:217], s[88:89], 0, v[210:211]
	global_load_dwordx4 v[176:179], v[214:215], off
	global_load_dwordx4 v[180:183], v[216:217], off
	v_lshl_add_u64 v[214:215], s[88:89], 0, v[212:213]
	v_lshl_add_u64 v[216:217], s[88:89], 0, v[204:205]
	global_load_dwordx4 v[184:187], v[214:215], off
	global_load_dwordx4 v[188:191], v[216:217], off
	v_lshl_add_u64 v[214:215], s[88:89], 0, v[206:207]
	global_load_dwordx4 v[192:195], v[214:215], off
.Lat_skipld:
	s_and_b32 s4, 1, s1
	s_cselect_b32 s5, 0, 0x5800
	v_add3_u32 v235, s5, v223, v198
	v_add_u32_e32 v218, s5, v224
	ds_read_b128 v[236:239], v235
	ds_read_b128 v[240:243], v235 offset:6656
	ds_read_b128 v[244:247], v235 offset:32
	ds_read_b128 v[248:251], v235 offset:6688
	s_waitcnt lgkmcnt(3)
	v_mfma_f32_32x32x16_bf16 v[64:79], v[236:239], v[128:131], 0
	v_mfma_f32_32x32x16_bf16 v[96:111], v[236:239], v[152:155], 0
	ds_read_b128 v[236:239], v235 offset:64
	s_waitcnt lgkmcnt(3)
	v_mfma_f32_32x32x16_bf16 v[80:95], v[240:243], v[128:131], 0
	v_mfma_f32_32x32x16_bf16 v[112:127], v[240:243], v[152:155], 0
	ds_read_b128 v[240:243], v235 offset:6720
	s_waitcnt lgkmcnt(3)
	v_mfma_f32_32x32x16_bf16 v[64:79], v[244:247], v[132:135], v[64:79]
	v_mfma_f32_32x32x16_bf16 v[96:111], v[244:247], v[156:159], v[96:111]
	ds_read_b128 v[244:247], v235 offset:96
	s_waitcnt lgkmcnt(3)
	v_mfma_f32_32x32x16_bf16 v[80:95], v[248:251], v[132:135], v[80:95]
	v_mfma_f32_32x32x16_bf16 v[112:127], v[248:251], v[156:159], v[112:127]
	ds_read_b128 v[248:251], v235 offset:6752
	s_waitcnt lgkmcnt(3)
	v_mfma_f32_32x32x16_bf16 v[64:79], v[236:239], v[136:139], v[64:79]
	v_mfma_f32_32x32x16_bf16 v[96:111], v[236:239], v[160:163], v[96:111]
	ds_read_b128 v[236:239], v235 offset:128
	s_waitcnt lgkmcnt(3)
	v_mfma_f32_32x32x16_bf16 v[80:95], v[240:243], v[136:139], v[80:95]
	v_mfma_f32_32x32x16_bf16 v[112:127], v[240:243], v[160:163], v[112:127]
	ds_read_b128 v[240:243], v235 offset:6784
	s_waitcnt lgkmcnt(3)
	v_mfma_f32_32x32x16_bf16 v[64:79], v[244:247], v[140:143], v[64:79]
	v_mfma_f32_32x32x16_bf16 v[96:111], v[244:247], v[164:167], v[96:111]
	ds_read_b128 v[244:247], v235 offset:160
	s_waitcnt lgkmcnt(3)
	v_mfma_f32_32x32x16_bf16 v[80:95], v[248:251], v[140:143], v[80:95]
	v_mfma_f32_32x32x16_bf16 v[112:127], v[248:251], v[164:167], v[112:127]
	ds_read_b128 v[248:251], v235 offset:6816
	s_waitcnt lgkmcnt(3)
	v_mfma_f32_32x32x16_bf16 v[64:79], v[236:239], v[144:147], v[64:79]
	v_mfma_f32_32x32x16_bf16 v[96:111], v[236:239], v[168:171], v[96:111]
	ds_read_b128 v[236:239], v218 offset:13312
	s_waitcnt lgkmcnt(3)
	v_mfma_f32_32x32x16_bf16 v[80:95], v[240:243], v[144:147], v[80:95]
	v_mfma_f32_32x32x16_bf16 v[112:127], v[240:243], v[168:171], v[112:127]
	ds_read_b128 v[240:243], v218 offset:17920
	s_waitcnt lgkmcnt(3)
	v_mfma_f32_32x32x16_bf16 v[64:79], v[244:247], v[148:151], v[64:79]
	v_mfma_f32_32x32x16_bf16 v[96:111], v[244:247], v[172:175], v[96:111]
	s_waitcnt lgkmcnt(2)
	v_mfma_f32_32x32x16_bf16 v[80:95], v[248:251], v[148:151], v[80:95]
	v_mfma_f32_32x32x16_bf16 v[112:127], v[248:251], v[172:175], v[112:127]
	ds_read_b128 v[244:247], v218 offset:13344
	ds_read_b128 v[248:251], v218 offset:17952
	s_nop 7
	s_nop 1
	v_max3_f32 v214, v64, v65, v66
	v_max3_f32 v215, v80, v81, v82
	v_max3_f32 v216, v96, v97, v98
	v_max3_f32 v217, v112, v113, v114
	v_max3_f32 v214, v214, v67, v68
	v_max3_f32 v215, v215, v83, v84
	v_max3_f32 v216, v216, v99, v100
	v_max3_f32 v217, v217, v115, v116
	v_max3_f32 v214, v214, v69, v70
	v_max3_f32 v215, v215, v85, v86
	v_max3_f32 v216, v216, v101, v102
	v_max3_f32 v217, v217, v117, v118
	v_max3_f32 v214, v214, v71, v72
	v_max3_f32 v215, v215, v87, v88
	v_max3_f32 v216, v216, v103, v104
	v_max3_f32 v217, v217, v119, v120
	v_max3_f32 v214, v214, v73, v74
	v_max3_f32 v215, v215, v89, v90
	v_max3_f32 v216, v216, v105, v106
	v_max3_f32 v217, v217, v121, v122
	v_max3_f32 v214, v214, v75, v76
	v_max3_f32 v215, v215, v91, v92
	v_max3_f32 v216, v216, v107, v108
	v_max3_f32 v217, v217, v123, v124
	v_max3_f32 v214, v214, v77, v78
	v_max3_f32 v215, v215, v93, v94
	v_max3_f32 v216, v216, v109, v110
	v_max3_f32 v217, v217, v125, v126
	v_max_f32_e32 v214, v214, v79
	v_max_f32_e32 v215, v215, v95
	v_max_f32_e32 v216, v216, v111
	v_max_f32_e32 v217, v217, v127
	v_max_f32_e32 v214, v214, v215
	v_max_f32_e32 v216, v216, v217
	ds_bpermute_b32 v215, v201, v214
	ds_bpermute_b32 v217, v201, v216
	s_waitcnt lgkmcnt(0)
	v_max_f32_e32 v214, v214, v215
	v_max_f32_e32 v216, v216, v217
	v_sub_f32_e32 v215, v214, v233
	v_sub_f32_e32 v217, v216, v234
	v_cmp_lt_f32_e32 vcc, s56, v215
	s_cbranch_vccz .Lat_nr0
	v_max_f32_e32 v215, v214, v233
	v_sub_f32_e32 v196, v233, v215
	v_exp_f32_e32 v196, v196
	v_mov_b32_e32 v233, v215
	s_nop 0
	v_mul_f32_e32 v202, v196, v202
	v_mul_f32_e32 v0, v196, v0
	v_mul_f32_e32 v1, v196, v1
	v_mul_f32_e32 v2, v196, v2
	v_mul_f32_e32 v3, v196, v3
	v_mul_f32_e32 v4, v196, v4
	v_mul_f32_e32 v5, v196, v5
	v_mul_f32_e32 v6, v196, v6
	v_mul_f32_e32 v7, v196, v7
	v_mul_f32_e32 v8, v196, v8
	v_mul_f32_e32 v9, v196, v9
	v_mul_f32_e32 v10, v196, v10
	v_mul_f32_e32 v11, v196, v11
	v_mul_f32_e32 v12, v196, v12
	v_mul_f32_e32 v13, v196, v13
	v_mul_f32_e32 v14, v196, v14
	v_mul_f32_e32 v15, v196, v15
	v_mul_f32_e32 v16, v196, v16
	v_mul_f32_e32 v17, v196, v17
	v_mul_f32_e32 v18, v196, v18
	v_mul_f32_e32 v19, v196, v19
	v_mul_f32_e32 v20, v196, v20
	v_mul_f32_e32 v21, v196, v21
	v_mul_f32_e32 v22, v196, v22
	v_mul_f32_e32 v23, v196, v23
	v_mul_f32_e32 v24, v196, v24
	v_mul_f32_e32 v25, v196, v25
	v_mul_f32_e32 v26, v196, v26
	v_mul_f32_e32 v27, v196, v27
	v_mul_f32_e32 v28, v196, v28
	v_mul_f32_e32 v29, v196, v29
	v_mul_f32_e32 v30, v196, v30
	v_mul_f32_e32 v31, v196, v31
.Lat_nr0:
	v_cmp_lt_f32_e32 vcc, s56, v217
	s_cbranch_vccz .Lat_nr1
	v_max_f32_e32 v217, v216, v234
	v_sub_f32_e32 v196, v234, v217
	v_exp_f32_e32 v196, v196
	v_mov_b32_e32 v234, v217
	s_nop 0
	v_mul_f32_e32 v203, v196, v203
	v_mul_f32_e32 v32, v196, v32
	v_mul_f32_e32 v33, v196, v33
	v_mul_f32_e32 v34, v196, v34
	v_mul_f32_e32 v35, v196, v35
	v_mul_f32_e32 v36, v196, v36
	v_mul_f32_e32 v37, v196, v37
	v_mul_f32_e32 v38, v196, v38
	v_mul_f32_e32 v39, v196, v39
	v_mul_f32_e32 v40, v196, v40
	v_mul_f32_e32 v41, v196, v41
	v_mul_f32_e32 v42, v196, v42
	v_mul_f32_e32 v43, v196, v43
	v_mul_f32_e32 v44, v196, v44
	v_mul_f32_e32 v45, v196, v45
	v_mul_f32_e32 v46, v196, v46
	v_mul_f32_e32 v47, v196, v47
	v_mul_f32_e32 v48, v196, v48
	v_mul_f32_e32 v49, v196, v49
	v_mul_f32_e32 v50, v196, v50
	v_mul_f32_e32 v51, v196, v51
	v_mul_f32_e32 v52, v196, v52
	v_mul_f32_e32 v53, v196, v53
	v_mul_f32_e32 v54, v196, v54
	v_mul_f32_e32 v55, v196, v55
	v_mul_f32_e32 v56, v196, v56
	v_mul_f32_e32 v57, v196, v57
	v_mul_f32_e32 v58, v196, v58
	v_mul_f32_e32 v59, v196, v59
	v_mul_f32_e32 v60, v196, v60
	v_mul_f32_e32 v61, v196, v61
	v_mul_f32_e32 v62, v196, v62
	v_mul_f32_e32 v63, v196, v63
.Lat_nr1:
	v_sub_f32_e32 v64, v64, v233
	v_sub_f32_e32 v65, v65, v233
	v_sub_f32_e32 v66, v66, v233
	v_sub_f32_e32 v67, v67, v233
	v_exp_f32_e32 v64, v64
	v_sub_f32_e32 v68, v68, v233
	v_exp_f32_e32 v65, v65
	v_sub_f32_e32 v69, v69, v233
	v_exp_f32_e32 v66, v66
	v_sub_f32_e32 v70, v70, v233
	v_exp_f32_e32 v67, v67
	v_add_f32_e32 v202, v202, v64
	v_sub_f32_e32 v71, v71, v233
	v_exp_f32_e32 v68, v68
	v_sub_f32_e32 v72, v72, v233
	v_exp_f32_e32 v69, v69
	v_add_f32_e32 v202, v202, v66
	v_sub_f32_e32 v73, v73, v233
	v_exp_f32_e32 v70, v70
	v_add_f32_e32 v214, v65, v67
	v_cvt_pk_bf16_f32 v64, v64, v65
	v_sub_f32_e32 v74, v74, v233
	v_exp_f32_e32 v71, v71
	v_add_f32_e32 v202, v202, v68
	v_sub_f32_e32 v75, v75, v233
	v_exp_f32_e32 v72, v72
	v_add_f32_e32 v214, v214, v69
	v_cvt_pk_bf16_f32 v65, v66, v67
	v_sub_f32_e32 v76, v76, v233
	v_exp_f32_e32 v73, v73
	v_add_f32_e32 v202, v202, v70
	v_sub_f32_e32 v77, v77, v233
	v_exp_f32_e32 v74, v74
	v_add_f32_e32 v214, v214, v71
	v_cvt_pk_bf16_f32 v66, v68, v69
	v_sub_f32_e32 v78, v78, v233
	v_exp_f32_e32 v75, v75
	v_add_f32_e32 v202, v202, v72
	v_sub_f32_e32 v79, v79, v233
	v_exp_f32_e32 v76, v76
	v_add_f32_e32 v214, v214, v73
	v_cvt_pk_bf16_f32 v67, v70, v71
	v_sub_f32_e32 v80, v80, v233
	v_exp_f32_e32 v77, v77
	v_add_f32_e32 v202, v202, v74
	v_sub_f32_e32 v81, v81, v233
	v_exp_f32_e32 v78, v78
	v_add_f32_e32 v214, v214, v75
	v_cvt_pk_bf16_f32 v68, v72, v73
	v_sub_f32_e32 v82, v82, v233
	v_exp_f32_e32 v79, v79
	v_add_f32_e32 v202, v202, v76
	v_sub_f32_e32 v83, v83, v233
	v_exp_f32_e32 v80, v80
	v_add_f32_e32 v214, v214, v77
	v_cvt_pk_bf16_f32 v69, v74, v75
	v_sub_f32_e32 v84, v84, v233
	v_exp_f32_e32 v81, v81
	v_add_f32_e32 v202, v202, v78
	v_sub_f32_e32 v85, v85, v233
	v_exp_f32_e32 v82, v82
	v_add_f32_e32 v214, v214, v79
	v_cvt_pk_bf16_f32 v70, v76, v77
	v_sub_f32_e32 v86, v86, v233
	v_exp_f32_e32 v83, v83
	v_add_f32_e32 v202, v202, v80
	v_sub_f32_e32 v87, v87, v233
	v_exp_f32_e32 v84, v84
	v_add_f32_e32 v214, v214, v81
	v_cvt_pk_bf16_f32 v71, v78, v79
	v_sub_f32_e32 v88, v88, v233
	v_exp_f32_e32 v85, v85
	v_add_f32_e32 v202, v202, v82
	v_sub_f32_e32 v89, v89, v233
	v_exp_f32_e32 v86, v86
	v_add_f32_e32 v214, v214, v83
	v_cvt_pk_bf16_f32 v72, v80, v81
	v_sub_f32_e32 v90, v90, v233
	v_exp_f32_e32 v87, v87
	v_add_f32_e32 v202, v202, v84
	v_sub_f32_e32 v91, v91, v233
	v_exp_f32_e32 v88, v88
	v_add_f32_e32 v214, v214, v85
	v_cvt_pk_bf16_f32 v73, v82, v83
	v_sub_f32_e32 v92, v92, v233
	v_exp_f32_e32 v89, v89
	v_add_f32_e32 v202, v202, v86
	v_sub_f32_e32 v93, v93, v233
	v_exp_f32_e32 v90, v90
	v_add_f32_e32 v214, v214, v87
	v_cvt_pk_bf16_f32 v74, v84, v85
	v_sub_f32_e32 v94, v94, v233
	v_exp_f32_e32 v91, v91
	v_add_f32_e32 v202, v202, v88
	v_sub_f32_e32 v95, v95, v233
	v_exp_f32_e32 v92, v92
	v_add_f32_e32 v214, v214, v89
	v_cvt_pk_bf16_f32 v75, v86, v87
	v_exp_f32_e32 v93, v93
	v_add_f32_e32 v202, v202, v90
	v_exp_f32_e32 v94, v94
	v_add_f32_e32 v214, v214, v91
	v_cvt_pk_bf16_f32 v76, v88, v89
	v_exp_f32_e32 v95, v95
	v_add_f32_e32 v202, v202, v92
	v_add_f32_e32 v214, v214, v93
	v_cvt_pk_bf16_f32 v77, v90, v91
	v_add_f32_e32 v202, v202, v94
	v_add_f32_e32 v214, v214, v95
	v_cvt_pk_bf16_f32 v78, v92, v93
	v_cvt_pk_bf16_f32 v79, v94, v95
	v_add_f32_e32 v202, v202, v214
	ds_read_b128 v[80:83], v218 offset:13376
	ds_read_b128 v[84:87], v218 offset:17984
	ds_read_b128 v[88:91], v218 offset:13408
	ds_read_b128 v[92:95], v218 offset:18016
	s_nop 0
	v_mfma_f32_32x32x16_bf16 v[16:31], v[236:239], v[64:67], v[16:31]
	v_sub_f32_e32 v96, v96, v234
	v_sub_f32_e32 v97, v97, v234
	v_sub_f32_e32 v98, v98, v234
	v_sub_f32_e32 v99, v99, v234
	v_exp_f32_e32 v96, v96
	v_sub_f32_e32 v100, v100, v234
	v_exp_f32_e32 v97, v97
	v_sub_f32_e32 v101, v101, v234
	v_exp_f32_e32 v98, v98
	v_sub_f32_e32 v102, v102, v234
	v_exp_f32_e32 v99, v99
	v_add_f32_e32 v203, v203, v96
	v_sub_f32_e32 v103, v103, v234
	v_exp_f32_e32 v100, v100
	v_mfma_f32_32x32x16_bf16 v[0:15], v[240:243], v[64:67], v[0:15]
	v_sub_f32_e32 v104, v104, v234
	v_exp_f32_e32 v101, v101
	v_add_f32_e32 v203, v203, v98
	v_sub_f32_e32 v105, v105, v234
	v_exp_f32_e32 v102, v102
	v_add_f32_e32 v216, v97, v99
	v_cvt_pk_bf16_f32 v96, v96, v97
	v_sub_f32_e32 v106, v106, v234
	v_exp_f32_e32 v103, v103
	v_add_f32_e32 v203, v203, v100
	v_sub_f32_e32 v107, v107, v234
	v_exp_f32_e32 v104, v104
	v_add_f32_e32 v216, v216, v101
	v_cvt_pk_bf16_f32 v97, v98, v99
	v_mfma_f32_32x32x16_bf16 v[16:31], v[244:247], v[68:71], v[16:31]
	v_sub_f32_e32 v108, v108, v234
	v_exp_f32_e32 v105, v105
	v_add_f32_e32 v203, v203, v102
	v_sub_f32_e32 v109, v109, v234
	v_exp_f32_e32 v106, v106
	v_add_f32_e32 v216, v216, v103
	v_cvt_pk_bf16_f32 v98, v100, v101
	v_sub_f32_e32 v110, v110, v234
	v_exp_f32_e32 v107, v107
	v_add_f32_e32 v203, v203, v104
	v_sub_f32_e32 v111, v111, v234
	v_exp_f32_e32 v108, v108
	v_add_f32_e32 v216, v216, v105
	v_cvt_pk_bf16_f32 v99, v102, v103
	v_mfma_f32_32x32x16_bf16 v[0:15], v[248:251], v[68:71], v[0:15]
	v_sub_f32_e32 v112, v112, v234
	v_exp_f32_e32 v109, v109
	v_add_f32_e32 v203, v203, v106
	v_sub_f32_e32 v113, v113, v234
	v_exp_f32_e32 v110, v110
	v_add_f32_e32 v216, v216, v107
	v_cvt_pk_bf16_f32 v100, v104, v105
	v_sub_f32_e32 v114, v114, v234
	v_exp_f32_e32 v111, v111
	v_add_f32_e32 v203, v203, v108
	v_sub_f32_e32 v115, v115, v234
	v_exp_f32_e32 v112, v112
	v_add_f32_e32 v216, v216, v109
	v_cvt_pk_bf16_f32 v101, v106, v107
	s_waitcnt lgkmcnt(3)
	v_mfma_f32_32x32x16_bf16 v[16:31], v[80:83], v[72:75], v[16:31]
	v_sub_f32_e32 v116, v116, v234
	v_exp_f32_e32 v113, v113
	v_add_f32_e32 v203, v203, v110
	v_sub_f32_e32 v117, v117, v234
	v_exp_f32_e32 v114, v114
	v_add_f32_e32 v216, v216, v111
	v_cvt_pk_bf16_f32 v102, v108, v109
	v_sub_f32_e32 v118, v118, v234
	v_exp_f32_e32 v115, v115
	v_add_f32_e32 v203, v203, v112
	v_sub_f32_e32 v119, v119, v234
	v_exp_f32_e32 v116, v116
	v_add_f32_e32 v216, v216, v113
	v_cvt_pk_bf16_f32 v103, v110, v111
	s_waitcnt lgkmcnt(2)
	v_mfma_f32_32x32x16_bf16 v[0:15], v[84:87], v[72:75], v[0:15]
	v_sub_f32_e32 v120, v120, v234
	v_exp_f32_e32 v117, v117
	v_add_f32_e32 v203, v203, v114
	v_sub_f32_e32 v121, v121, v234
	v_exp_f32_e32 v118, v118
	v_add_f32_e32 v216, v216, v115
	v_cvt_pk_bf16_f32 v104, v112, v113
	v_sub_f32_e32 v122, v122, v234
	v_exp_f32_e32 v119, v119
	v_add_f32_e32 v203, v203, v116
	v_sub_f32_e32 v123, v123, v234
	v_exp_f32_e32 v120, v120
	v_add_f32_e32 v216, v216, v117
	v_cvt_pk_bf16_f32 v105, v114, v115
	s_waitcnt lgkmcnt(1)
	v_mfma_f32_32x32x16_bf16 v[16:31], v[88:91], v[76:79], v[16:31]
	v_sub_f32_e32 v124, v124, v234
	v_exp_f32_e32 v121, v121
	v_add_f32_e32 v203, v203, v118
	v_sub_f32_e32 v125, v125, v234
	v_exp_f32_e32 v122, v122
	v_add_f32_e32 v216, v216, v119
	v_cvt_pk_bf16_f32 v106, v116, v117
	v_sub_f32_e32 v126, v126, v234
	v_exp_f32_e32 v123, v123
	v_add_f32_e32 v203, v203, v120
	v_sub_f32_e32 v127, v127, v234
	v_exp_f32_e32 v124, v124
	v_add_f32_e32 v216, v216, v121
	v_cvt_pk_bf16_f32 v107, v118, v119
	s_waitcnt lgkmcnt(0)
	v_mfma_f32_32x32x16_bf16 v[0:15], v[92:95], v[76:79], v[0:15]
	v_exp_f32_e32 v125, v125
	v_add_f32_e32 v203, v203, v122
	v_exp_f32_e32 v126, v126
	v_add_f32_e32 v216, v216, v123
	v_cvt_pk_bf16_f32 v108, v120, v121
	v_exp_f32_e32 v127, v127
	v_add_f32_e32 v203, v203, v124
	v_add_f32_e32 v216, v216, v125
	v_cvt_pk_bf16_f32 v109, v122, v123
	v_add_f32_e32 v203, v203, v126
	v_add_f32_e32 v216, v216, v127
	v_cvt_pk_bf16_f32 v110, v124, v125
	v_cvt_pk_bf16_f32 v111, v126, v127
	v_add_f32_e32 v203, v203, v216
	s_nop 0
	v_mfma_f32_32x32x16_bf16 v[48:63], v[236:239], v[96:99], v[48:63]
	v_mfma_f32_32x32x16_bf16 v[32:47], v[240:243], v[96:99], v[32:47]
	s_cmp_eq_u32 s1, 64
	s_cbranch_scc1 .Lat_nowr
	s_cmp_eq_u32 s4, 1
	s_cselect_b32 s4, 0x5800, 0
	v_add3_u32 v214, s4, v225, v226
	v_add3_u32 v215, s4, v227, v228
	v_add3_u32 v216, s4, v229, v230
	v_add3_u32 v217, s4, v231, v200
	v_add3_u32 v196, s4, v232, v200
	s_waitcnt vmcnt(4)
	ds_write_b128 v214, v[176:179]
	s_waitcnt vmcnt(3)
	ds_write_b128 v215, v[180:183]
	s_waitcnt vmcnt(2)
	ds_write_b128 v216, v[184:187]
	s_waitcnt vmcnt(1)
	ds_write_b128 v217, v[188:191] offset:13312
	s_waitcnt vmcnt(0)
	ds_write_b128 v196, v[192:195] offset:13312
.Lat_nowr:
	v_mfma_f32_32x32x16_bf16 v[48:63], v[244:247], v[100:103], v[48:63]
	v_mfma_f32_32x32x16_bf16 v[32:47], v[248:251], v[100:103], v[32:47]
	v_mfma_f32_32x32x16_bf16 v[48:63], v[80:83], v[104:107], v[48:63]
	v_mfma_f32_32x32x16_bf16 v[32:47], v[84:87], v[104:107], v[32:47]
	v_mfma_f32_32x32x16_bf16 v[48:63], v[88:91], v[108:111], v[48:63]
	v_mfma_f32_32x32x16_bf16 v[32:47], v[92:95], v[108:111], v[32:47]
	s_add_i32 s1, s1, 1
	v_lshl_add_u64 v[204:205], v[204:205], 0, s[76:77]
	v_lshl_add_u64 v[206:207], v[206:207], 0, s[76:77]
	v_lshl_add_u64 v[208:209], v[208:209], 0, s[54:55]
	v_lshl_add_u64 v[210:211], v[210:211], 0, s[54:55]
	v_lshl_add_u64 v[212:213], v[212:213], 0, s[54:55]
	s_cmpk_eq_i32 s1, 0x41
	s_waitcnt lgkmcnt(0)
	s_barrier
	s_cbranch_scc0 .LBB0_346
	s_nop 7
	s_nop 7
	s_branch .LBB0_343
